# v20 + branch layout in the two diff-attention main loops: rare bias/rescale blocks moved out of line, common path falls through (8 sites)
# baseline (speedup 1.0000x reference)
.LBB0_1088:
	v_add_u32_e32 v0, s6, v204
	ds_read_b64_tr_b16 v[174:175], v0 offset:32768
	ds_read_b64_tr_b16 v[176:177], v0 offset:33280
	s_add_i32 s6, s42, 0xffffe000
	s_and_b32 s54, s6, 0x6000
	v_add_u32_e32 v130, s54, v201
	s_waitcnt lgkmcnt(2)
	v_mfma_f32_32x32x16_bf16 v[114:129], v[114:117], v[158:161], 0
	v_add_f32_e32 v98, v82, v83
	v_add_f32_e32 v98, v84, v98
	v_add_f32_e32 v98, v85, v98
	v_add_f32_e32 v98, v86, v98
	v_add_f32_e32 v98, v87, v98
	v_cvt_pk_bf16_f32 v142, v82, v83
	v_cvt_pk_bf16_f32 v143, v84, v85
	ds_read_b64_tr_b16 v[82:83], v0 offset:36864
	ds_read_b64_tr_b16 v[84:85], v0 offset:37376
	v_add_f32_e32 v98, v88, v98
	v_add_f32_e32 v98, v89, v98
	v_add_f32_e32 v98, v90, v98
	v_add_f32_e32 v131, v91, v98
	v_mfma_f32_32x32x16_bf16 v[98:113], v[170:173], v[158:161], 0
	v_cvt_pk_bf16_f32 v144, v86, v87
	v_cvt_pk_bf16_f32 v145, v88, v89
	ds_read_b128 v[170:173], v130 offset:4096
	ds_read_b128 v[206:209], v130 offset:4608
	ds_read_b64_tr_b16 v[86:87], v0 offset:33792
	ds_read_b64_tr_b16 v[88:89], v0 offset:34304
	v_mfma_f32_32x32x16_bf16 v[114:129], v[166:169], v[154:157], v[114:129]
	v_add_f32_e32 v131, v92, v131
	v_add_f32_e32 v131, v93, v131
	v_add_f32_e32 v131, v94, v131
	v_add_f32_e32 v131, v95, v131
	v_cvt_pk_bf16_f32 v138, v90, v91
	v_cvt_pk_bf16_f32 v139, v92, v93
	ds_read_b64_tr_b16 v[90:91], v0 offset:37888
	ds_read_b64_tr_b16 v[92:93], v0 offset:38400
	v_mfma_f32_32x32x16_bf16 v[98:113], v[162:165], v[154:157], v[98:113]
	v_add_f32_e32 v131, v96, v131
	v_add_f32_e32 v131, v97, v131
	v_add_f32_e32 v131, v66, v131
	v_add_f32_e32 v131, v67, v131
	v_cvt_pk_bf16_f32 v140, v94, v95
	v_cvt_pk_bf16_f32 v141, v96, v97
	ds_read_b128 v[162:165], v130 offset:6144
	ds_read_b128 v[166:169], v130 offset:6656
	ds_read_b64_tr_b16 v[94:95], v0 offset:34816
	ds_read_b64_tr_b16 v[96:97], v0 offset:35328
	s_waitcnt lgkmcnt(9)
	v_mfma_f32_32x32x16_bf16 v[114:129], v[170:173], v[150:153], v[114:129]
	v_add_f32_e32 v130, v68, v131
	v_add_f32_e32 v130, v69, v130
	v_add_f32_e32 v130, v70, v130
	v_add_f32_e32 v130, v71, v130
	v_cvt_pk_bf16_f32 v134, v66, v67
	v_cvt_pk_bf16_f32 v135, v68, v69
	ds_read_b64_tr_b16 v[66:67], v0 offset:38912
	ds_read_b64_tr_b16 v[68:69], v0 offset:39424
	s_waitcnt lgkmcnt(10)
	v_mfma_f32_32x32x16_bf16 v[98:113], v[206:209], v[150:153], v[98:113]
	v_add_f32_e32 v130, v72, v130
	v_add_f32_e32 v130, v73, v130
	v_add_f32_e32 v130, v74, v130
	v_add_f32_e32 v130, v75, v130
	v_cvt_pk_bf16_f32 v136, v70, v71
	v_cvt_pk_bf16_f32 v137, v72, v73
	ds_read_b64_tr_b16 v[70:71], v0 offset:35840
	ds_read_b64_tr_b16 v[72:73], v0 offset:36352
	s_waitcnt lgkmcnt(7)
	v_mfma_f32_32x32x16_bf16 v[114:129], v[162:165], v[146:149], v[114:129]
	v_add_f32_e32 v130, v76, v130
	v_add_f32_e32 v130, v77, v130
	v_add_f32_e32 v130, v78, v130
	v_add_f32_e32 v170, v79, v130
	v_cvt_pk_bf16_f32 v130, v74, v75
	v_cvt_pk_bf16_f32 v131, v76, v77
	ds_read_b64_tr_b16 v[74:75], v0 offset:39936
	ds_read_b64_tr_b16 v[76:77], v0 offset:40448
	s_waitcnt lgkmcnt(8)
	v_mfma_f32_32x32x16_bf16 v[98:113], v[166:169], v[146:149], v[98:113]
	v_add_f32_e32 v132, v80, v170
	v_add_f32_e32 v132, v81, v132
	v_add_f32_e32 v162, 0, v132
	v_cvt_pk_bf16_f32 v132, v78, v79
	v_cvt_pk_bf16_f32 v133, v80, v81
	s_add_u32 s87, s44, s8
	s_addc_u32 s88, s45, s9
	s_add_u32 s6, s87, 0x80000
	s_addc_u32 s7, s88, 0
	s_add_i32 s16, s42, 0x4000
	s_and_b32 s12, s16, 0x6000
	s_add_i32 s12, s12, s33
	s_add_u32 s85, s71, s8
	s_addc_u32 s86, s73, s9
	s_mov_b32 m0, s12
	s_nop 0
	global_load_lds_dwordx4 v202, s[6:7]
	s_add_u32 s6, s85, 0x22040000
	s_addc_u32 s7, s86, 0
	s_add_i32 s12, s11, s59
	s_add_u32 s90, s85, 0x22040080
	s_mov_b32 m0, s12
	s_nop 0
	global_load_lds_dwordx4 v203, s[6:7]
	s_addc_u32 s91, s86, 0
	s_addk_i32 s12, 0x2000
	s_cmp_ge_i32 s10, s57
	s_cselect_b64 s[92:93], -1, 0
	s_cmp_gt_i32 s58, s10
	s_cselect_b64 s[6:7], -1, 0
	s_mov_b32 m0, s12
	s_nop 0
	global_load_lds_dwordx4 v203, s[90:91]
	s_and_b64 s[92:93], s[92:93], s[6:7]
	s_andn2_b64 vcc, exec, s[92:93]
	s_cbranch_vccz .Lrare_1088_0
.LBB0_1090:
	s_add_i32 s43, s74, s10
	v_add_f32_e32 v178, v178, v162
	v_mfma_f32_32x32x16_bf16 v[50:65], v[142:145], v[174:177], v[50:65]
	v_exp_f32_e32 v114, v114
	v_exp_f32_e32 v115, v115
	ds_read_b64_tr_b16 v[78:79], v0 offset:40960
	ds_read_b64_tr_b16 v[80:81], v0 offset:41472
	v_mfma_f32_32x32x16_bf16 v[34:49], v[142:145], v[82:85], v[34:49]
	v_exp_f32_e32 v116, v116
	v_exp_f32_e32 v117, v117
	ds_read_b64_tr_b16 v[82:83], v0 offset:45056
	ds_read_b64_tr_b16 v[84:85], v0 offset:45568
	v_mfma_f32_32x32x16_bf16 v[50:65], v[138:141], v[86:89], v[50:65]
	v_exp_f32_e32 v118, v118
	v_exp_f32_e32 v119, v119
	ds_read_b64_tr_b16 v[86:87], v0 offset:41984
	ds_read_b64_tr_b16 v[88:89], v0 offset:42496
	v_mfma_f32_32x32x16_bf16 v[34:49], v[138:141], v[90:93], v[34:49]
	v_exp_f32_e32 v120, v120
	v_exp_f32_e32 v121, v121
	ds_read_b64_tr_b16 v[90:91], v0 offset:46080
	ds_read_b64_tr_b16 v[92:93], v0 offset:46592
	s_waitcnt lgkmcnt(14)
	v_mfma_f32_32x32x16_bf16 v[50:65], v[134:137], v[94:97], v[50:65]
	v_exp_f32_e32 v122, v122
	v_exp_f32_e32 v123, v123
	ds_read_b64_tr_b16 v[94:95], v0 offset:43008
	ds_read_b64_tr_b16 v[96:97], v0 offset:43520
	s_waitcnt lgkmcnt(14)
	v_mfma_f32_32x32x16_bf16 v[34:49], v[134:137], v[66:69], v[34:49]
	v_exp_f32_e32 v124, v124
	v_exp_f32_e32 v125, v125
	ds_read_b64_tr_b16 v[170:171], v0 offset:47104
	ds_read_b64_tr_b16 v[172:173], v0 offset:47616
	s_waitcnt lgkmcnt(14)
	v_mfma_f32_32x32x16_bf16 v[50:65], v[130:133], v[70:73], v[50:65]
	v_exp_f32_e32 v126, v126
	v_exp_f32_e32 v127, v127
	ds_read_b64_tr_b16 v[206:207], v0 offset:44032
	ds_read_b64_tr_b16 v[208:209], v0 offset:44544
	s_waitcnt lgkmcnt(14)
;   #define RSCALE(t) do{ if(HAS_BIAS&&((t)==tn0||(t)==tn1)){ const float f_=__builtin_amdgcn_exp2f(CREG((t)-1)-CREG(t)); l_reg*=f_; \
;     _Pragma("unroll") for(int d_=0;d_<2*VH;++d_) _Pragma("unroll") for(int r=0;r<16;++r)o[d_][r]*=f_; } }while(0)
;   #define ROT() do{sv_prev=sv_cur;sv_cur=sv_next;sv_next=(sv_next==2*VSL)?0:sv_next+VSL;}while(0)
;   #define WAITFULL() do{ if(VH==1){WAIT_BAR(2);}else{WAIT_BAR(3);} }while(0)
; template<int VH,bool HAS_BIAS,int MODE> __device__ __forceinline__ void attn_unit2(const bf16*Qb,int qp,const bf16*__restrict__ Kb,int kp,const bf16*__restrict__ Vb,int vp,bf16*Ob,int op,int q0,int NT,const float*relb,char*shm,float lam,const float*subg,float gmul){
;     ...
;   int t=1;
;   for(;t+5<NT;t+=2){
;     STEP(pB0,pB1,pA0,pA1,t,true,true,true);     WAITFULL(); RSCALE(t);   ROT();
;     STEP(pA0,pA1,pB0,pB1,t+1,true,true,true);   WAITFULL(); RSCALE(t+1); ROT();
	v_mfma_f32_32x32x16_bf16 v[34:49], v[130:133], v[74:77], v[34:49]
	v_exp_f32_e32 v128, v128
	v_exp_f32_e32 v129, v129
	ds_read_b64_tr_b16 v[74:75], v0 offset:48128
	ds_read_b64_tr_b16 v[76:77], v0 offset:48640
	s_and_b32 s12, s42, 0x6000
	v_add_u32_e32 v175, s12, v201
	ds_read_b128 v[70:73], v175
	ds_read_b128 v[66:69], v175 offset:512
	ds_read_b128 v[166:169], v175 offset:2048
	ds_read_b128 v[162:165], v175 offset:2560
	s_waitcnt lgkmcnt(14)
	v_mfma_f32_32x32x16_bf16 v[18:33], v[142:145], v[78:81], v[18:33]
	v_exp_f32_e32 v98, v98
	v_exp_f32_e32 v99, v99
	v_mfma_f32_32x32x16_bf16 v[2:17], v[142:145], v[82:85], v[2:17]
	v_exp_f32_e32 v100, v100
	v_exp_f32_e32 v101, v101
	v_mfma_f32_32x32x16_bf16 v[18:33], v[138:141], v[86:89], v[18:33]
	v_exp_f32_e32 v102, v102
	v_exp_f32_e32 v103, v103
	s_waitcnt lgkmcnt(12)
	v_mfma_f32_32x32x16_bf16 v[2:17], v[138:141], v[90:93], v[2:17]
	v_exp_f32_e32 v104, v104
	v_exp_f32_e32 v105, v105
	s_waitcnt lgkmcnt(10)
	v_mfma_f32_32x32x16_bf16 v[18:33], v[134:137], v[94:97], v[18:33]
	v_exp_f32_e32 v106, v106
	v_exp_f32_e32 v107, v107
	s_waitcnt lgkmcnt(8)
	v_mfma_f32_32x32x16_bf16 v[2:17], v[134:137], v[170:173], v[2:17]
	v_exp_f32_e32 v108, v108
	v_exp_f32_e32 v109, v109
	s_waitcnt lgkmcnt(6)
	v_mfma_f32_32x32x16_bf16 v[18:33], v[130:133], v[206:209], v[18:33]
	v_exp_f32_e32 v110, v110
	v_exp_f32_e32 v111, v111
	s_waitcnt lgkmcnt(4)
	v_mfma_f32_32x32x16_bf16 v[2:17], v[130:133], v[74:77], v[2:17]
	v_exp_f32_e32 v112, v112
	v_exp_f32_e32 v113, v113
	s_cmp_eq_u32 s57, s10
	s_cselect_b64 s[90:91], -1, 0
	s_cmp_eq_u32 s43, 0
	s_waitcnt vmcnt(3) lgkmcnt(0)
	s_barrier
	s_cselect_b64 s[92:93], -1, 0
	s_or_b64 s[90:91], s[90:91], s[92:93]
	s_andn2_b64 vcc, exec, s[90:91]
	v_cndmask_b32_e64 v0, v199, 0, s[6:7]
	s_cbranch_vccz .Lrare_1088_1
.LBB0_1092:
	s_add_i32 s89, s10, 1
	s_add_i32 s6, s11, 0x4000
	s_cmpk_lg_u32 s11, 0x8000
	s_cselect_b32 s83, s6, 0
	v_add_u32_e32 v174, s55, v204
	ds_read_b64_tr_b16 v[170:171], v174 offset:32768
	ds_read_b64_tr_b16 v[172:173], v174 offset:33280
	s_waitcnt lgkmcnt(5)
	v_mfma_f32_32x32x16_bf16 v[82:97], v[70:73], v[158:161], 0
	v_add_f32_e32 v74, v114, v115
	v_add_f32_e32 v74, v116, v74
	v_add_f32_e32 v74, v117, v74
	v_add_f32_e32 v74, v118, v74
	v_add_f32_e32 v74, v119, v74
	v_cvt_pk_bf16_f32 v142, v114, v115
	v_cvt_pk_bf16_f32 v143, v116, v117
	ds_read_b64_tr_b16 v[114:115], v174 offset:36864
	ds_read_b64_tr_b16 v[116:117], v174 offset:37376
	v_add_f32_e32 v70, v120, v74
	v_add_f32_e32 v70, v121, v70
	v_add_f32_e32 v70, v122, v70
	v_add_f32_e32 v130, v123, v70
	s_waitcnt lgkmcnt(6)
	v_mfma_f32_32x32x16_bf16 v[66:81], v[66:69], v[158:161], 0
	v_cvt_pk_bf16_f32 v144, v118, v119
	v_cvt_pk_bf16_f32 v145, v120, v121
	ds_read_b128 v[206:209], v175 offset:4096
	ds_read_b128 v[210:213], v175 offset:4608
	ds_read_b64_tr_b16 v[118:119], v174 offset:33792
	ds_read_b64_tr_b16 v[120:121], v174 offset:34304
	s_waitcnt lgkmcnt(9)
	v_mfma_f32_32x32x16_bf16 v[82:97], v[166:169], v[154:157], v[82:97]
	v_add_f32_e32 v130, v124, v130
	v_add_f32_e32 v130, v125, v130
	v_add_f32_e32 v130, v126, v130
	v_add_f32_e32 v130, v127, v130
	v_cvt_pk_bf16_f32 v138, v122, v123
	v_cvt_pk_bf16_f32 v139, v124, v125
	ds_read_b64_tr_b16 v[122:123], v174 offset:37888
	ds_read_b64_tr_b16 v[124:125], v174 offset:38400
	s_waitcnt lgkmcnt(10)
	v_mfma_f32_32x32x16_bf16 v[66:81], v[162:165], v[154:157], v[66:81]
	v_add_f32_e32 v130, v128, v130
	v_add_f32_e32 v130, v129, v130
	v_add_f32_e32 v130, v98, v130
	v_add_f32_e32 v130, v99, v130
	v_cvt_pk_bf16_f32 v140, v126, v127
	v_cvt_pk_bf16_f32 v141, v128, v129
	ds_read_b128 v[162:165], v175 offset:6144
	ds_read_b128 v[166:169], v175 offset:6656
	ds_read_b64_tr_b16 v[126:127], v174 offset:34816
	ds_read_b64_tr_b16 v[128:129], v174 offset:35328
	s_waitcnt lgkmcnt(9)
	v_mfma_f32_32x32x16_bf16 v[82:97], v[206:209], v[150:153], v[82:97]
	v_add_f32_e32 v130, v100, v130
	v_add_f32_e32 v130, v101, v130
	v_add_f32_e32 v130, v102, v130
	v_add_f32_e32 v130, v103, v130
	v_cvt_pk_bf16_f32 v134, v98, v99
	v_cvt_pk_bf16_f32 v135, v100, v101
	ds_read_b64_tr_b16 v[98:99], v174 offset:38912
	ds_read_b64_tr_b16 v[100:101], v174 offset:39424
	s_waitcnt lgkmcnt(10)
	v_mfma_f32_32x32x16_bf16 v[66:81], v[210:213], v[150:153], v[66:81]
	v_add_f32_e32 v130, v104, v130
	v_add_f32_e32 v130, v105, v130
	v_add_f32_e32 v130, v106, v130
	v_add_f32_e32 v130, v107, v130
	v_cvt_pk_bf16_f32 v136, v102, v103
	v_cvt_pk_bf16_f32 v137, v104, v105
	ds_read_b64_tr_b16 v[102:103], v174 offset:35840
	ds_read_b64_tr_b16 v[104:105], v174 offset:36352
	s_waitcnt lgkmcnt(7)
	v_mfma_f32_32x32x16_bf16 v[82:97], v[162:165], v[146:149], v[82:97]
	v_add_f32_e32 v130, v108, v130
	v_add_f32_e32 v130, v109, v130
	v_add_f32_e32 v130, v110, v130
	v_add_f32_e32 v175, v111, v130
	v_cvt_pk_bf16_f32 v130, v106, v107
	v_cvt_pk_bf16_f32 v131, v108, v109
	ds_read_b64_tr_b16 v[106:107], v174 offset:39936
	ds_read_b64_tr_b16 v[108:109], v174 offset:40448
	s_waitcnt lgkmcnt(8)
	v_mfma_f32_32x32x16_bf16 v[66:81], v[166:169], v[146:149], v[66:81]
	v_add_f32_e32 v132, v112, v175
	v_add_f32_e32 v132, v113, v132
	v_add_f32_e32 v162, 0, v132
	v_cvt_pk_bf16_f32 v132, v110, v111
	v_cvt_pk_bf16_f32 v133, v112, v113
	s_add_u32 s6, s87, 0xa0000
	s_addc_u32 s7, s88, 0
	s_add_i32 s12, s54, s33
	s_mov_b32 m0, s12
	s_nop 0
	global_load_lds_dwordx4 v202, s[6:7]
	s_add_u32 s6, s85, 0x22060000
	s_addc_u32 s7, s86, 0
	s_add_i32 s12, s83, s59
	s_add_u32 s54, s85, 0x22060080
	s_mov_b32 m0, s12
	s_nop 0
	global_load_lds_dwordx4 v203, s[6:7]
	s_addc_u32 s55, s86, 0
	s_addk_i32 s12, 0x2000
	s_cmp_ge_i32 s89, s57
	s_cselect_b64 s[86:87], -1, 0
	s_cmp_lt_i32 s89, s60
	s_cselect_b64 s[6:7], -1, 0
	s_mov_b32 m0, s12
	s_nop 0
	global_load_lds_dwordx4 v203, s[54:55]
	s_and_b64 s[86:87], s[86:87], s[6:7]
	s_andn2_b64 vcc, exec, s[86:87]
	s_cbranch_vccz .Lrare_1088_2
;   #define RSCALE(t) do{ if(HAS_BIAS&&((t)==tn0||(t)==tn1)){ const float f_=__builtin_amdgcn_exp2f(CREG((t)-1)-CREG(t)); l_reg*=f_; \
;     _Pragma("unroll") for(int d_=0;d_<2*VH;++d_) _Pragma("unroll") for(int r=0;r<16;++r)o[d_][r]*=f_; } }while(0)
;   #define ROT() do{sv_prev=sv_cur;sv_cur=sv_next;sv_next=(sv_next==2*VSL)?0:sv_next+VSL;}while(0)
;   #define WAITFULL() do{ if(VH==1){WAIT_BAR(2);}else{WAIT_BAR(3);} }while(0)
; template<int VH,bool HAS_BIAS,int MODE> __device__ __forceinline__ void attn_unit2(const bf16*Qb,int qp,const bf16*__restrict__ Kb,int kp,const bf16*__restrict__ Vb,int vp,bf16*Ob,int op,int q0,int NT,const float*relb,char*shm,float lam,const float*subg,float gmul){
;     ...
;   int t=1;
;   for(;t+5<NT;t+=2){
;     STEP(pB0,pB1,pA0,pA1,t,true,true,true);     WAITFULL(); RSCALE(t);   ROT();
;     STEP(pA0,pA1,pB0,pB1,t+1,true,true,true);   WAITFULL(); RSCALE(t+1); ROT();
.LBB0_1094:
	v_add_f32_e32 v178, v178, v162
	s_add_i32 s54, s81, s10
	v_mfma_f32_32x32x16_bf16 v[50:65], v[142:145], v[170:173], v[50:65]
	v_exp_f32_e32 v82, v82
	v_exp_f32_e32 v83, v83
	ds_read_b64_tr_b16 v[110:111], v174 offset:40960
	ds_read_b64_tr_b16 v[112:113], v174 offset:41472
	v_mfma_f32_32x32x16_bf16 v[34:49], v[142:145], v[114:117], v[34:49]
	v_exp_f32_e32 v84, v84
	v_exp_f32_e32 v85, v85
	ds_read_b64_tr_b16 v[206:207], v174 offset:45056
	ds_read_b64_tr_b16 v[208:209], v174 offset:45568
	v_mfma_f32_32x32x16_bf16 v[50:65], v[138:141], v[118:121], v[50:65]
	v_exp_f32_e32 v86, v86
	v_exp_f32_e32 v87, v87
	ds_read_b64_tr_b16 v[118:119], v174 offset:41984
	ds_read_b64_tr_b16 v[120:121], v174 offset:42496
	v_mfma_f32_32x32x16_bf16 v[34:49], v[138:141], v[122:125], v[34:49]
	v_exp_f32_e32 v88, v88
	v_exp_f32_e32 v89, v89
	ds_read_b64_tr_b16 v[122:123], v174 offset:46080
	ds_read_b64_tr_b16 v[124:125], v174 offset:46592
	s_waitcnt lgkmcnt(14)
	v_mfma_f32_32x32x16_bf16 v[50:65], v[134:137], v[126:129], v[50:65]
	v_exp_f32_e32 v90, v90
	v_exp_f32_e32 v91, v91
	ds_read_b64_tr_b16 v[126:127], v174 offset:43008
	ds_read_b64_tr_b16 v[128:129], v174 offset:43520
	s_waitcnt lgkmcnt(14)
	v_mfma_f32_32x32x16_bf16 v[34:49], v[134:137], v[98:101], v[34:49]
	v_exp_f32_e32 v92, v92
	v_exp_f32_e32 v93, v93
	ds_read_b64_tr_b16 v[98:99], v174 offset:47104
	ds_read_b64_tr_b16 v[100:101], v174 offset:47616
	s_waitcnt lgkmcnt(14)
	v_mfma_f32_32x32x16_bf16 v[50:65], v[130:133], v[102:105], v[50:65]
	v_exp_f32_e32 v94, v94
	v_exp_f32_e32 v95, v95
	ds_read_b64_tr_b16 v[102:103], v174 offset:44032
	ds_read_b64_tr_b16 v[104:105], v174 offset:44544
	s_waitcnt lgkmcnt(14)
	v_mfma_f32_32x32x16_bf16 v[34:49], v[130:133], v[106:109], v[34:49]
	v_exp_f32_e32 v96, v96
	v_exp_f32_e32 v97, v97
	ds_read_b64_tr_b16 v[106:107], v174 offset:48128
	ds_read_b64_tr_b16 v[108:109], v174 offset:48640
	s_add_i32 s12, s42, 0x2000
	s_and_b32 s12, s12, 0x6000
	v_add_u32_e32 v162, s12, v201
	ds_read_b128 v[114:117], v162
	ds_read_b128 v[170:173], v162 offset:512
	ds_read_b128 v[166:169], v162 offset:2048
	ds_read_b128 v[162:165], v162 offset:2560
	s_waitcnt lgkmcnt(14)
	v_mfma_f32_32x32x16_bf16 v[18:33], v[142:145], v[110:113], v[18:33]
	v_exp_f32_e32 v66, v66
	v_exp_f32_e32 v67, v67
	v_mfma_f32_32x32x16_bf16 v[2:17], v[142:145], v[206:209], v[2:17]
	v_exp_f32_e32 v68, v68
	v_exp_f32_e32 v69, v69
	v_mfma_f32_32x32x16_bf16 v[18:33], v[138:141], v[118:121], v[18:33]
	v_exp_f32_e32 v70, v70
	v_exp_f32_e32 v71, v71
	s_waitcnt lgkmcnt(12)
	v_mfma_f32_32x32x16_bf16 v[2:17], v[138:141], v[122:125], v[2:17]
	v_exp_f32_e32 v72, v72
	v_exp_f32_e32 v73, v73
	s_waitcnt lgkmcnt(10)
	v_mfma_f32_32x32x16_bf16 v[18:33], v[134:137], v[126:129], v[18:33]
	v_exp_f32_e32 v74, v74
	v_exp_f32_e32 v75, v75
	s_waitcnt lgkmcnt(8)
	v_mfma_f32_32x32x16_bf16 v[2:17], v[134:137], v[98:101], v[2:17]
	v_exp_f32_e32 v76, v76
	v_exp_f32_e32 v77, v77
	s_waitcnt lgkmcnt(6)
	v_mfma_f32_32x32x16_bf16 v[18:33], v[130:133], v[102:105], v[18:33]
	v_exp_f32_e32 v78, v78
	v_exp_f32_e32 v79, v79
	s_waitcnt lgkmcnt(4)
	v_mfma_f32_32x32x16_bf16 v[2:17], v[130:133], v[106:109], v[2:17]
	v_exp_f32_e32 v80, v80
	v_exp_f32_e32 v81, v81
	s_cmp_eq_u32 s54, -1
	s_cselect_b64 s[54:55], -1, 0
	s_cmp_eq_u32 s43, -1
	s_cselect_b64 s[42:43], -1, 0
	s_waitcnt vmcnt(3) lgkmcnt(0)
	s_barrier
	s_or_b64 s[42:43], s[54:55], s[42:43]
	s_andn2_b64 vcc, exec, s[42:43]
	s_cbranch_vccz .Lrare_1088_3

.Lrare_1088_0:
	ds_read2_b32 v[78:79], v179 offset1:1
	ds_read2_b32 v[80:81], v179 offset0:2 offset1:3
	ds_read2_b32 v[164:165], v179 offset0:8 offset1:9
	ds_read2_b32 v[166:167], v179 offset0:10 offset1:11
	ds_read2_b32 v[168:169], v179 offset0:16 offset1:17
	ds_read2_b32 v[170:171], v179 offset0:18 offset1:19
	ds_read2_b32 v[172:173], v179 offset0:24 offset1:25
	ds_read2_b32 v[180:181], v179 offset0:26 offset1:27
	ds_read2_b32 v[206:207], v179 offset0:32 offset1:33
	ds_read2_b32 v[208:209], v179 offset0:34 offset1:35
	ds_read2_b32 v[210:211], v179 offset0:40 offset1:41
	ds_read2_b32 v[212:213], v179 offset0:42 offset1:43
	s_waitcnt lgkmcnt(11)
	v_pk_add_f32 v[114:115], v[114:115], v[78:79]
	s_waitcnt lgkmcnt(5)
	v_pk_add_f32 v[126:127], v[126:127], v[172:173]
	v_pk_add_f32 v[124:125], v[124:125], v[170:171]
	v_pk_add_f32 v[122:123], v[122:123], v[168:169]
	ds_read2_b32 v[78:79], v179 offset0:48 offset1:49
	ds_read2_b32 v[168:169], v179 offset0:50 offset1:51
	ds_read2_b32 v[170:171], v179 offset0:56 offset1:57
	ds_read2_b32 v[172:173], v179 offset0:58 offset1:59
	s_waitcnt lgkmcnt(8)
	v_pk_add_f32 v[128:129], v[128:129], v[180:181]
	v_pk_add_f32 v[120:121], v[120:121], v[166:167]
	v_pk_add_f32 v[118:119], v[118:119], v[164:165]
	v_pk_add_f32 v[116:117], v[116:117], v[80:81]
	s_waitcnt lgkmcnt(7)
	v_pk_add_f32 v[98:99], v[98:99], v[206:207]
	s_waitcnt lgkmcnt(0)
	v_pk_add_f32 v[112:113], v[112:113], v[172:173]
	v_pk_add_f32 v[110:111], v[110:111], v[170:171]
	v_pk_add_f32 v[108:109], v[108:109], v[168:169]
	v_pk_add_f32 v[106:107], v[106:107], v[78:79]
	v_pk_add_f32 v[104:105], v[104:105], v[212:213]
	v_pk_add_f32 v[102:103], v[102:103], v[210:211]
	v_pk_add_f32 v[100:101], v[100:101], v[208:209]
	s_branch .LBB0_1090
.Lrare_1088_1:
	s_cmp_gt_i32 s10, s57
	s_cselect_b64 vcc, -1, 0
	s_cmp_gt_i32 s10, s60
	s_cselect_b64 s[6:7], -1, 0
	v_cndmask_b32_e64 v74, 0, v199, s[6:7]
	s_cmp_lt_i32 s10, s57
	v_cndmask_b32_e32 v74, v198, v74, vcc
	s_cselect_b64 vcc, -1, 0
	v_cndmask_b32_e32 v75, v0, v198, vcc
	v_sub_f32_e32 v74, v74, v75
	v_exp_f32_e32 v74, v74
	s_nop 0
	v_pk_mul_f32 v[64:65], v[74:75], v[64:65] op_sel_hi:[0,1]
	v_pk_mul_f32 v[62:63], v[74:75], v[62:63] op_sel_hi:[0,1]
	v_pk_mul_f32 v[60:61], v[74:75], v[60:61] op_sel_hi:[0,1]
	v_pk_mul_f32 v[58:59], v[74:75], v[58:59] op_sel_hi:[0,1]
	v_pk_mul_f32 v[56:57], v[74:75], v[56:57] op_sel_hi:[0,1]
	v_pk_mul_f32 v[54:55], v[74:75], v[54:55] op_sel_hi:[0,1]
	v_pk_mul_f32 v[52:53], v[74:75], v[52:53] op_sel_hi:[0,1]
	v_pk_mul_f32 v[50:51], v[74:75], v[50:51] op_sel_hi:[0,1]
	v_pk_mul_f32 v[48:49], v[74:75], v[48:49] op_sel_hi:[0,1]
	v_pk_mul_f32 v[46:47], v[74:75], v[46:47] op_sel_hi:[0,1]
	v_pk_mul_f32 v[44:45], v[74:75], v[44:45] op_sel_hi:[0,1]
	v_pk_mul_f32 v[42:43], v[74:75], v[42:43] op_sel_hi:[0,1]
	v_pk_mul_f32 v[40:41], v[74:75], v[40:41] op_sel_hi:[0,1]
	v_pk_mul_f32 v[38:39], v[74:75], v[38:39] op_sel_hi:[0,1]
	v_pk_mul_f32 v[36:37], v[74:75], v[36:37] op_sel_hi:[0,1]
	v_pk_mul_f32 v[34:35], v[74:75], v[34:35] op_sel_hi:[0,1]
	v_pk_mul_f32 v[32:33], v[74:75], v[32:33] op_sel_hi:[0,1]
	v_pk_mul_f32 v[30:31], v[74:75], v[30:31] op_sel_hi:[0,1]
	v_pk_mul_f32 v[28:29], v[74:75], v[28:29] op_sel_hi:[0,1]
	v_pk_mul_f32 v[26:27], v[74:75], v[26:27] op_sel_hi:[0,1]
	v_pk_mul_f32 v[24:25], v[74:75], v[24:25] op_sel_hi:[0,1]
	v_pk_mul_f32 v[22:23], v[74:75], v[22:23] op_sel_hi:[0,1]
	v_pk_mul_f32 v[20:21], v[74:75], v[20:21] op_sel_hi:[0,1]
	v_pk_mul_f32 v[18:19], v[74:75], v[18:19] op_sel_hi:[0,1]
	v_pk_mul_f32 v[16:17], v[74:75], v[16:17] op_sel_hi:[0,1]
	v_pk_mul_f32 v[14:15], v[74:75], v[14:15] op_sel_hi:[0,1]
	v_pk_mul_f32 v[12:13], v[74:75], v[12:13] op_sel_hi:[0,1]
	v_pk_mul_f32 v[10:11], v[74:75], v[10:11] op_sel_hi:[0,1]
	v_pk_mul_f32 v[8:9], v[74:75], v[8:9] op_sel_hi:[0,1]
	v_pk_mul_f32 v[6:7], v[74:75], v[6:7] op_sel_hi:[0,1]
	v_pk_mul_f32 v[4:5], v[74:75], v[4:5] op_sel_hi:[0,1]
	v_pk_mul_f32 v[2:3], v[74:75], v[2:3] op_sel_hi:[0,1]
	v_mul_f32_e32 v178, v74, v178
	s_branch .LBB0_1092
;   #define RSCALE(t) do{ if(HAS_BIAS&&((t)==tn0||(t)==tn1)){ const float f_=__builtin_amdgcn_exp2f(CREG((t)-1)-CREG(t)); l_reg*=f_; \
;     _Pragma("unroll") for(int d_=0;d_<2*VH;++d_) _Pragma("unroll") for(int r=0;r<16;++r)o[d_][r]*=f_; } }while(0)
;   #define ROT() do{sv_prev=sv_cur;sv_cur=sv_next;sv_next=(sv_next==2*VSL)?0:sv_next+VSL;}while(0)
;   #define WAITFULL() do{ if(VH==1){WAIT_BAR(2);}else{WAIT_BAR(3);} }while(0)
; template<int VH,bool HAS_BIAS,int MODE> __device__ __forceinline__ void attn_unit2(const bf16*Qb,int qp,const bf16*__restrict__ Kb,int kp,const bf16*__restrict__ Vb,int vp,bf16*Ob,int op,int q0,int NT,const float*relb,char*shm,float lam,const float*subg,float gmul){
;     ...
;   for(;t+5<NT;t+=2){
;     STEP(pB0,pB1,pA0,pA1,t,true,true,true);     WAITFULL(); RSCALE(t);   ROT();
;     STEP(pA0,pA1,pB0,pB1,t+1,true,true,true);   WAITFULL(); RSCALE(t+1); ROT();
.Lrare_1088_2:
	ds_read2_b32 v[110:111], v179 offset0:64 offset1:65
	ds_read2_b32 v[112:113], v179 offset0:66 offset1:67
	ds_read2_b32 v[164:165], v179 offset0:72 offset1:73
	ds_read2_b32 v[166:167], v179 offset0:74 offset1:75
	ds_read2_b32 v[168:169], v179 offset0:80 offset1:81
	ds_read2_b32 v[176:177], v179 offset0:82 offset1:83
	ds_read2_b32 v[180:181], v179 offset0:88 offset1:89
	ds_read2_b32 v[206:207], v179 offset0:90 offset1:91
	ds_read2_b32 v[208:209], v179 offset0:96 offset1:97
	ds_read2_b32 v[210:211], v179 offset0:98 offset1:99
	ds_read2_b32 v[212:213], v179 offset0:104 offset1:105
	ds_read2_b32 v[214:215], v179 offset0:106 offset1:107
	s_waitcnt lgkmcnt(11)
	v_pk_add_f32 v[82:83], v[82:83], v[110:111]
	s_waitcnt lgkmcnt(5)
	v_pk_add_f32 v[94:95], v[94:95], v[180:181]
	v_pk_add_f32 v[92:93], v[92:93], v[176:177]
	v_pk_add_f32 v[90:91], v[90:91], v[168:169]
	ds_read2_b32 v[110:111], v179 offset0:112 offset1:113
	ds_read2_b32 v[168:169], v179 offset0:114 offset1:115
	ds_read2_b32 v[176:177], v179 offset0:120 offset1:121
	ds_read2_b32 v[180:181], v179 offset0:122 offset1:123
	s_waitcnt lgkmcnt(8)
	v_pk_add_f32 v[96:97], v[96:97], v[206:207]
	v_pk_add_f32 v[88:89], v[88:89], v[166:167]
	v_pk_add_f32 v[86:87], v[86:87], v[164:165]
	v_pk_add_f32 v[84:85], v[84:85], v[112:113]
	s_waitcnt lgkmcnt(7)
	v_pk_add_f32 v[66:67], v[66:67], v[208:209]
	s_waitcnt lgkmcnt(0)
	v_pk_add_f32 v[80:81], v[80:81], v[180:181]
	v_pk_add_f32 v[78:79], v[78:79], v[176:177]
	v_pk_add_f32 v[76:77], v[76:77], v[168:169]
	v_pk_add_f32 v[74:75], v[74:75], v[110:111]
	v_pk_add_f32 v[72:73], v[72:73], v[214:215]
	v_pk_add_f32 v[70:71], v[70:71], v[212:213]
	v_pk_add_f32 v[68:69], v[68:69], v[210:211]
	s_branch .LBB0_1094
.Lrare_1088_3:
	s_cmp_lt_i32 s10, s57
	s_cselect_b64 vcc, -1, 0
	s_cmp_lt_i32 s89, s57
	v_cndmask_b32_e32 v0, v0, v198, vcc
	v_cndmask_b32_e64 v98, v199, 0, s[6:7]
	s_cselect_b64 vcc, -1, 0
	v_cndmask_b32_e32 v98, v98, v198, vcc
	v_sub_f32_e32 v0, v0, v98
	v_exp_f32_e32 v0, v0
	s_nop 0
	v_pk_mul_f32 v[64:65], v[0:1], v[64:65] op_sel_hi:[0,1]
	v_pk_mul_f32 v[62:63], v[0:1], v[62:63] op_sel_hi:[0,1]
	v_pk_mul_f32 v[60:61], v[0:1], v[60:61] op_sel_hi:[0,1]
	v_pk_mul_f32 v[58:59], v[0:1], v[58:59] op_sel_hi:[0,1]
	v_pk_mul_f32 v[56:57], v[0:1], v[56:57] op_sel_hi:[0,1]
	v_pk_mul_f32 v[54:55], v[0:1], v[54:55] op_sel_hi:[0,1]
	v_pk_mul_f32 v[52:53], v[0:1], v[52:53] op_sel_hi:[0,1]
	v_pk_mul_f32 v[50:51], v[0:1], v[50:51] op_sel_hi:[0,1]
	v_pk_mul_f32 v[48:49], v[0:1], v[48:49] op_sel_hi:[0,1]
	v_pk_mul_f32 v[46:47], v[0:1], v[46:47] op_sel_hi:[0,1]
	v_pk_mul_f32 v[44:45], v[0:1], v[44:45] op_sel_hi:[0,1]
	v_pk_mul_f32 v[42:43], v[0:1], v[42:43] op_sel_hi:[0,1]
	v_pk_mul_f32 v[40:41], v[0:1], v[40:41] op_sel_hi:[0,1]
	v_pk_mul_f32 v[38:39], v[0:1], v[38:39] op_sel_hi:[0,1]
	v_pk_mul_f32 v[36:37], v[0:1], v[36:37] op_sel_hi:[0,1]
	v_pk_mul_f32 v[34:35], v[0:1], v[34:35] op_sel_hi:[0,1]
	v_pk_mul_f32 v[32:33], v[0:1], v[32:33] op_sel_hi:[0,1]
	v_pk_mul_f32 v[30:31], v[0:1], v[30:31] op_sel_hi:[0,1]
	v_pk_mul_f32 v[28:29], v[0:1], v[28:29] op_sel_hi:[0,1]
	v_pk_mul_f32 v[26:27], v[0:1], v[26:27] op_sel_hi:[0,1]
	v_pk_mul_f32 v[24:25], v[0:1], v[24:25] op_sel_hi:[0,1]
	v_pk_mul_f32 v[22:23], v[0:1], v[22:23] op_sel_hi:[0,1]
	v_pk_mul_f32 v[20:21], v[0:1], v[20:21] op_sel_hi:[0,1]
	v_pk_mul_f32 v[18:19], v[0:1], v[18:19] op_sel_hi:[0,1]
	v_pk_mul_f32 v[16:17], v[0:1], v[16:17] op_sel_hi:[0,1]
	v_pk_mul_f32 v[14:15], v[0:1], v[14:15] op_sel_hi:[0,1]
	v_pk_mul_f32 v[12:13], v[0:1], v[12:13] op_sel_hi:[0,1]
	v_pk_mul_f32 v[10:11], v[0:1], v[10:11] op_sel_hi:[0,1]
	v_pk_mul_f32 v[8:9], v[0:1], v[8:9] op_sel_hi:[0,1]
	v_pk_mul_f32 v[6:7], v[0:1], v[6:7] op_sel_hi:[0,1]
	v_pk_mul_f32 v[4:5], v[0:1], v[4:5] op_sel_hi:[0,1]
	v_pk_mul_f32 v[2:3], v[0:1], v[2:3] op_sel_hi:[0,1]
	v_mul_f32_e32 v178, v0, v178
	s_branch .LBB0_1096

.LBB0_1156:
	v_add_u32_e32 v0, s6, v208
	ds_read_b64_tr_b16 v[174:175], v0 offset:32768
	ds_read_b64_tr_b16 v[176:177], v0 offset:33280
	s_add_i32 s6, s47, 0xffffe000
	s_and_b32 s60, s6, 0x6000
	v_add_u32_e32 v130, s60, v205
	s_waitcnt lgkmcnt(2)
	v_mfma_f32_32x32x16_bf16 v[114:129], v[114:117], v[158:161], 0
	v_add_f32_e32 v98, v82, v83
	v_add_f32_e32 v98, v84, v98
	v_add_f32_e32 v98, v85, v98
	v_add_f32_e32 v98, v86, v98
	v_add_f32_e32 v98, v87, v98
	v_cvt_pk_bf16_f32 v142, v82, v83
	v_cvt_pk_bf16_f32 v143, v84, v85
	ds_read_b64_tr_b16 v[82:83], v0 offset:36864
	ds_read_b64_tr_b16 v[84:85], v0 offset:37376
	v_add_f32_e32 v98, v88, v98
	v_add_f32_e32 v98, v89, v98
	v_add_f32_e32 v98, v90, v98
	v_add_f32_e32 v131, v91, v98
	v_mfma_f32_32x32x16_bf16 v[98:113], v[170:173], v[158:161], 0
	v_cvt_pk_bf16_f32 v144, v86, v87
	v_cvt_pk_bf16_f32 v145, v88, v89
	ds_read_b128 v[170:173], v130 offset:4096
	ds_read_b128 v[210:213], v130 offset:4608
	ds_read_b64_tr_b16 v[86:87], v0 offset:33792
	ds_read_b64_tr_b16 v[88:89], v0 offset:34304
	v_mfma_f32_32x32x16_bf16 v[114:129], v[166:169], v[154:157], v[114:129]
	v_add_f32_e32 v131, v92, v131
	v_add_f32_e32 v131, v93, v131
	v_add_f32_e32 v131, v94, v131
	v_add_f32_e32 v131, v95, v131
	v_cvt_pk_bf16_f32 v138, v90, v91
	v_cvt_pk_bf16_f32 v139, v92, v93
	ds_read_b64_tr_b16 v[90:91], v0 offset:37888
	ds_read_b64_tr_b16 v[92:93], v0 offset:38400
	v_mfma_f32_32x32x16_bf16 v[98:113], v[162:165], v[154:157], v[98:113]
	v_add_f32_e32 v131, v96, v131
	v_add_f32_e32 v131, v97, v131
	v_add_f32_e32 v131, v66, v131
	v_add_f32_e32 v131, v67, v131
	v_cvt_pk_bf16_f32 v140, v94, v95
	v_cvt_pk_bf16_f32 v141, v96, v97
	ds_read_b128 v[162:165], v130 offset:6144
	ds_read_b128 v[166:169], v130 offset:6656
	ds_read_b64_tr_b16 v[94:95], v0 offset:34816
	ds_read_b64_tr_b16 v[96:97], v0 offset:35328
	s_waitcnt lgkmcnt(9)
	v_mfma_f32_32x32x16_bf16 v[114:129], v[170:173], v[150:153], v[114:129]
	v_add_f32_e32 v130, v68, v131
	v_add_f32_e32 v130, v69, v130
	v_add_f32_e32 v130, v70, v130
	v_add_f32_e32 v130, v71, v130
	v_cvt_pk_bf16_f32 v134, v66, v67
	v_cvt_pk_bf16_f32 v135, v68, v69
	ds_read_b64_tr_b16 v[66:67], v0 offset:38912
	ds_read_b64_tr_b16 v[68:69], v0 offset:39424
	s_waitcnt lgkmcnt(10)
	v_mfma_f32_32x32x16_bf16 v[98:113], v[210:213], v[150:153], v[98:113]
	v_add_f32_e32 v130, v72, v130
	v_add_f32_e32 v130, v73, v130
	v_add_f32_e32 v130, v74, v130
	v_add_f32_e32 v130, v75, v130
	v_cvt_pk_bf16_f32 v136, v70, v71
	v_cvt_pk_bf16_f32 v137, v72, v73
	ds_read_b64_tr_b16 v[70:71], v0 offset:35840
	ds_read_b64_tr_b16 v[72:73], v0 offset:36352
	s_waitcnt lgkmcnt(7)
	v_mfma_f32_32x32x16_bf16 v[114:129], v[162:165], v[146:149], v[114:129]
	v_add_f32_e32 v130, v76, v130
	v_add_f32_e32 v130, v77, v130
	v_add_f32_e32 v130, v78, v130
	v_add_f32_e32 v170, v79, v130
	v_cvt_pk_bf16_f32 v130, v74, v75
	v_cvt_pk_bf16_f32 v131, v76, v77
	ds_read_b64_tr_b16 v[74:75], v0 offset:39936
	ds_read_b64_tr_b16 v[76:77], v0 offset:40448
	s_waitcnt lgkmcnt(8)
	v_mfma_f32_32x32x16_bf16 v[98:113], v[166:169], v[146:149], v[98:113]
	v_add_f32_e32 v132, v80, v170
	v_add_f32_e32 v132, v81, v132
	v_add_f32_e32 v162, 0, v132
	v_cvt_pk_bf16_f32 v132, v78, v79
	v_cvt_pk_bf16_f32 v133, v80, v81
	s_add_u32 s77, s8, s40
	s_addc_u32 s78, s9, s41
	s_add_u32 s6, s77, 0x80000
	s_addc_u32 s7, s78, 0
	s_add_i32 s46, s47, 0x4000
	s_and_b32 s12, s46, 0x6000
	s_add_i32 s12, s12, s33
	s_add_u32 s75, s71, s40
	s_addc_u32 s76, s73, s41
	s_mov_b32 m0, s12
	s_nop 0
	global_load_lds_dwordx4 v206, s[6:7]
	s_add_u32 s6, s75, 0x22040000
	s_addc_u32 s7, s76, 0
	s_add_i32 s14, s45, s57
	s_mov_b32 m0, s14
	s_nop 0
	global_load_lds_dwordx4 v207, s[6:7]
	s_add_u32 s12, s75, 0x22040080
	s_addc_u32 s13, s76, 0
	s_addk_i32 s14, 0x2000
	s_cmp_ge_i32 s44, s55
	s_cselect_b64 s[82:83], -1, 0
	s_cmp_gt_i32 s56, s44
	s_cselect_b64 s[6:7], -1, 0
	s_mov_b32 m0, s14
	s_nop 0
	global_load_lds_dwordx4 v207, s[12:13]
	s_and_b64 s[82:83], s[82:83], s[6:7]
	s_andn2_b64 vcc, exec, s[82:83]
	s_cbranch_vccz .Lrare_1156_0
.LBB0_1158:
	s_add_i32 s59, s49, s44
	v_add_f32_e32 v178, v178, v162
	v_mfma_f32_32x32x16_bf16 v[50:65], v[142:145], v[174:177], v[50:65]
	v_exp_f32_e32 v114, v114
	v_exp_f32_e32 v115, v115
	ds_read_b64_tr_b16 v[78:79], v0 offset:40960
	ds_read_b64_tr_b16 v[80:81], v0 offset:41472
	v_mfma_f32_32x32x16_bf16 v[34:49], v[142:145], v[82:85], v[34:49]
	v_exp_f32_e32 v116, v116
	v_exp_f32_e32 v117, v117
	ds_read_b64_tr_b16 v[82:83], v0 offset:45056
	ds_read_b64_tr_b16 v[84:85], v0 offset:45568
	v_mfma_f32_32x32x16_bf16 v[50:65], v[138:141], v[86:89], v[50:65]
	v_exp_f32_e32 v118, v118
	v_exp_f32_e32 v119, v119
	ds_read_b64_tr_b16 v[86:87], v0 offset:41984
	ds_read_b64_tr_b16 v[88:89], v0 offset:42496
	v_mfma_f32_32x32x16_bf16 v[34:49], v[138:141], v[90:93], v[34:49]
	v_exp_f32_e32 v120, v120
	v_exp_f32_e32 v121, v121
	ds_read_b64_tr_b16 v[90:91], v0 offset:46080
	ds_read_b64_tr_b16 v[92:93], v0 offset:46592
	s_waitcnt lgkmcnt(14)
	v_mfma_f32_32x32x16_bf16 v[50:65], v[134:137], v[94:97], v[50:65]
	v_exp_f32_e32 v122, v122
	v_exp_f32_e32 v123, v123
	ds_read_b64_tr_b16 v[94:95], v0 offset:43008
	ds_read_b64_tr_b16 v[96:97], v0 offset:43520
	s_waitcnt lgkmcnt(14)
	v_mfma_f32_32x32x16_bf16 v[34:49], v[134:137], v[66:69], v[34:49]
	v_exp_f32_e32 v124, v124
	v_exp_f32_e32 v125, v125
	ds_read_b64_tr_b16 v[170:171], v0 offset:47104
	ds_read_b64_tr_b16 v[172:173], v0 offset:47616
	s_waitcnt lgkmcnt(14)
	v_mfma_f32_32x32x16_bf16 v[50:65], v[130:133], v[70:73], v[50:65]
	v_exp_f32_e32 v126, v126
	v_exp_f32_e32 v127, v127
	ds_read_b64_tr_b16 v[210:211], v0 offset:44032
	ds_read_b64_tr_b16 v[212:213], v0 offset:44544
	s_waitcnt lgkmcnt(14)
;   #define RSCALE(t) do{ if(HAS_BIAS&&((t)==tn0||(t)==tn1)){ const float f_=__builtin_amdgcn_exp2f(CREG((t)-1)-CREG(t)); l_reg*=f_; \
;     _Pragma("unroll") for(int d_=0;d_<2*VH;++d_) _Pragma("unroll") for(int r=0;r<16;++r)o[d_][r]*=f_; } }while(0)
;   #define ROT() do{sv_prev=sv_cur;sv_cur=sv_next;sv_next=(sv_next==2*VSL)?0:sv_next+VSL;}while(0)
;   #define WAITFULL() do{ if(VH==1){WAIT_BAR(2);}else{WAIT_BAR(3);} }while(0)
; template<int VH,bool HAS_BIAS,int MODE> __device__ __forceinline__ void attn_unit2(const bf16*Qb,int qp,const bf16*__restrict__ Kb,int kp,const bf16*__restrict__ Vb,int vp,bf16*Ob,int op,int q0,int NT,const float*relb,char*shm,float lam,const float*subg,float gmul){
;     ...
;   int t=1;
;   for(;t+5<NT;t+=2){
;     STEP(pB0,pB1,pA0,pA1,t,true,true,true);     WAITFULL(); RSCALE(t);   ROT();
;     STEP(pA0,pA1,pB0,pB1,t+1,true,true,true);   WAITFULL(); RSCALE(t+1); ROT();
	v_mfma_f32_32x32x16_bf16 v[34:49], v[130:133], v[74:77], v[34:49]
	v_exp_f32_e32 v128, v128
	v_exp_f32_e32 v129, v129
	ds_read_b64_tr_b16 v[74:75], v0 offset:48128
	ds_read_b64_tr_b16 v[76:77], v0 offset:48640
	s_and_b32 s12, s47, 0x6000
	v_add_u32_e32 v175, s12, v205
	ds_read_b128 v[70:73], v175
	ds_read_b128 v[66:69], v175 offset:512
	ds_read_b128 v[166:169], v175 offset:2048
	ds_read_b128 v[162:165], v175 offset:2560
	s_waitcnt lgkmcnt(14)
	v_mfma_f32_32x32x16_bf16 v[18:33], v[142:145], v[78:81], v[18:33]
	v_exp_f32_e32 v98, v98
	v_exp_f32_e32 v99, v99
	v_mfma_f32_32x32x16_bf16 v[2:17], v[142:145], v[82:85], v[2:17]
	v_exp_f32_e32 v100, v100
	v_exp_f32_e32 v101, v101
	v_mfma_f32_32x32x16_bf16 v[18:33], v[138:141], v[86:89], v[18:33]
	v_exp_f32_e32 v102, v102
	v_exp_f32_e32 v103, v103
	s_waitcnt lgkmcnt(12)
	v_mfma_f32_32x32x16_bf16 v[2:17], v[138:141], v[90:93], v[2:17]
	v_exp_f32_e32 v104, v104
	v_exp_f32_e32 v105, v105
	s_waitcnt lgkmcnt(10)
	v_mfma_f32_32x32x16_bf16 v[18:33], v[134:137], v[94:97], v[18:33]
	v_exp_f32_e32 v106, v106
	v_exp_f32_e32 v107, v107
	s_waitcnt lgkmcnt(8)
	v_mfma_f32_32x32x16_bf16 v[2:17], v[134:137], v[170:173], v[2:17]
	v_exp_f32_e32 v108, v108
	v_exp_f32_e32 v109, v109
	s_waitcnt lgkmcnt(6)
	v_mfma_f32_32x32x16_bf16 v[18:33], v[130:133], v[210:213], v[18:33]
	v_exp_f32_e32 v110, v110
	v_exp_f32_e32 v111, v111
	s_waitcnt lgkmcnt(4)
	v_mfma_f32_32x32x16_bf16 v[2:17], v[130:133], v[74:77], v[2:17]
	v_exp_f32_e32 v112, v112
	v_exp_f32_e32 v113, v113
	s_cmp_eq_u32 s55, s44
	s_cselect_b64 s[12:13], -1, 0
	s_cmp_eq_u32 s59, 0
	s_waitcnt vmcnt(3) lgkmcnt(0)
	s_barrier
	s_cselect_b64 s[82:83], -1, 0
	s_or_b64 s[12:13], s[12:13], s[82:83]
	s_andn2_b64 vcc, exec, s[12:13]
	v_cndmask_b32_e64 v0, v203, 0, s[6:7]
	s_cbranch_vccz .Lrare_1156_1
.LBB0_1160:
	s_add_i32 s79, s44, 1
	s_add_i32 s6, s45, 0x4000
	s_cmpk_lg_u32 s45, 0x8000
	s_cselect_b32 s53, s6, 0
	v_add_u32_e32 v174, s61, v208
	ds_read_b64_tr_b16 v[170:171], v174 offset:32768
	ds_read_b64_tr_b16 v[172:173], v174 offset:33280
	s_waitcnt lgkmcnt(5)
	v_mfma_f32_32x32x16_bf16 v[82:97], v[70:73], v[158:161], 0
	v_add_f32_e32 v74, v114, v115
	v_add_f32_e32 v74, v116, v74
	v_add_f32_e32 v74, v117, v74
	v_add_f32_e32 v74, v118, v74
	v_add_f32_e32 v74, v119, v74
	v_cvt_pk_bf16_f32 v142, v114, v115
	v_cvt_pk_bf16_f32 v143, v116, v117
	ds_read_b64_tr_b16 v[114:115], v174 offset:36864
	ds_read_b64_tr_b16 v[116:117], v174 offset:37376
	v_add_f32_e32 v70, v120, v74
	v_add_f32_e32 v70, v121, v70
	v_add_f32_e32 v70, v122, v70
	v_add_f32_e32 v130, v123, v70
	s_waitcnt lgkmcnt(6)
	v_mfma_f32_32x32x16_bf16 v[66:81], v[66:69], v[158:161], 0
	v_cvt_pk_bf16_f32 v144, v118, v119
	v_cvt_pk_bf16_f32 v145, v120, v121
	ds_read_b128 v[210:213], v175 offset:4096
	ds_read_b128 v[214:217], v175 offset:4608
	ds_read_b64_tr_b16 v[118:119], v174 offset:33792
	ds_read_b64_tr_b16 v[120:121], v174 offset:34304
	s_waitcnt lgkmcnt(9)
	v_mfma_f32_32x32x16_bf16 v[82:97], v[166:169], v[154:157], v[82:97]
	v_add_f32_e32 v130, v124, v130
	v_add_f32_e32 v130, v125, v130
	v_add_f32_e32 v130, v126, v130
	v_add_f32_e32 v130, v127, v130
	v_cvt_pk_bf16_f32 v138, v122, v123
	v_cvt_pk_bf16_f32 v139, v124, v125
	ds_read_b64_tr_b16 v[122:123], v174 offset:37888
	ds_read_b64_tr_b16 v[124:125], v174 offset:38400
	s_waitcnt lgkmcnt(10)
	v_mfma_f32_32x32x16_bf16 v[66:81], v[162:165], v[154:157], v[66:81]
	v_add_f32_e32 v130, v128, v130
	v_add_f32_e32 v130, v129, v130
	v_add_f32_e32 v130, v98, v130
	v_add_f32_e32 v130, v99, v130
	v_cvt_pk_bf16_f32 v140, v126, v127
	v_cvt_pk_bf16_f32 v141, v128, v129
	ds_read_b128 v[162:165], v175 offset:6144
	ds_read_b128 v[166:169], v175 offset:6656
	ds_read_b64_tr_b16 v[126:127], v174 offset:34816
	ds_read_b64_tr_b16 v[128:129], v174 offset:35328
	s_waitcnt lgkmcnt(9)
	v_mfma_f32_32x32x16_bf16 v[82:97], v[210:213], v[150:153], v[82:97]
	v_add_f32_e32 v130, v100, v130
	v_add_f32_e32 v130, v101, v130
	v_add_f32_e32 v130, v102, v130
	v_add_f32_e32 v130, v103, v130
	v_cvt_pk_bf16_f32 v134, v98, v99
	v_cvt_pk_bf16_f32 v135, v100, v101
	ds_read_b64_tr_b16 v[98:99], v174 offset:38912
	ds_read_b64_tr_b16 v[100:101], v174 offset:39424
	s_waitcnt lgkmcnt(10)
	v_mfma_f32_32x32x16_bf16 v[66:81], v[214:217], v[150:153], v[66:81]
	v_add_f32_e32 v130, v104, v130
	v_add_f32_e32 v130, v105, v130
	v_add_f32_e32 v130, v106, v130
	v_add_f32_e32 v130, v107, v130
	v_cvt_pk_bf16_f32 v136, v102, v103
	v_cvt_pk_bf16_f32 v137, v104, v105
	ds_read_b64_tr_b16 v[102:103], v174 offset:35840
	ds_read_b64_tr_b16 v[104:105], v174 offset:36352
	s_waitcnt lgkmcnt(7)
	v_mfma_f32_32x32x16_bf16 v[82:97], v[162:165], v[146:149], v[82:97]
	v_add_f32_e32 v130, v108, v130
	v_add_f32_e32 v130, v109, v130
	v_add_f32_e32 v130, v110, v130
	v_add_f32_e32 v175, v111, v130
	v_cvt_pk_bf16_f32 v130, v106, v107
	v_cvt_pk_bf16_f32 v131, v108, v109
	ds_read_b64_tr_b16 v[106:107], v174 offset:39936
	ds_read_b64_tr_b16 v[108:109], v174 offset:40448
	s_waitcnt lgkmcnt(8)
	v_mfma_f32_32x32x16_bf16 v[66:81], v[166:169], v[146:149], v[66:81]
	v_add_f32_e32 v132, v112, v175
	v_add_f32_e32 v132, v113, v132
	v_add_f32_e32 v162, 0, v132
	v_cvt_pk_bf16_f32 v132, v110, v111
	v_cvt_pk_bf16_f32 v133, v112, v113
	s_add_u32 s6, s77, 0xa0000
	s_addc_u32 s7, s78, 0
	s_add_i32 s12, s60, s33
	s_mov_b32 m0, s12
	s_nop 0
	global_load_lds_dwordx4 v206, s[6:7]
	s_add_u32 s6, s75, 0x22060000
	s_addc_u32 s7, s76, 0
	s_add_i32 s14, s53, s57
	s_mov_b32 m0, s14
	s_nop 0
	global_load_lds_dwordx4 v207, s[6:7]
	s_add_u32 s12, s75, 0x22060080
	s_addc_u32 s13, s76, 0
	s_addk_i32 s14, 0x2000
	s_cmp_ge_i32 s79, s55
	s_cselect_b64 s[60:61], -1, 0
	s_cmp_lt_i32 s79, s48
	s_cselect_b64 s[6:7], -1, 0
	s_mov_b32 m0, s14
	s_nop 0
	global_load_lds_dwordx4 v207, s[12:13]
	s_and_b64 s[60:61], s[60:61], s[6:7]
	s_andn2_b64 vcc, exec, s[60:61]
	s_cbranch_vccz .Lrare_1156_2
;   #define RSCALE(t) do{ if(HAS_BIAS&&((t)==tn0||(t)==tn1)){ const float f_=__builtin_amdgcn_exp2f(CREG((t)-1)-CREG(t)); l_reg*=f_; \
;     _Pragma("unroll") for(int d_=0;d_<2*VH;++d_) _Pragma("unroll") for(int r=0;r<16;++r)o[d_][r]*=f_; } }while(0)
;   #define ROT() do{sv_prev=sv_cur;sv_cur=sv_next;sv_next=(sv_next==2*VSL)?0:sv_next+VSL;}while(0)
;   #define WAITFULL() do{ if(VH==1){WAIT_BAR(2);}else{WAIT_BAR(3);} }while(0)
; template<int VH,bool HAS_BIAS,int MODE> __device__ __forceinline__ void attn_unit2(const bf16*Qb,int qp,const bf16*__restrict__ Kb,int kp,const bf16*__restrict__ Vb,int vp,bf16*Ob,int op,int q0,int NT,const float*relb,char*shm,float lam,const float*subg,float gmul){
;     ...
;   int t=1;
;   for(;t+5<NT;t+=2){
;     STEP(pB0,pB1,pA0,pA1,t,true,true,true);     WAITFULL(); RSCALE(t);   ROT();
;     STEP(pA0,pA1,pB0,pB1,t+1,true,true,true);   WAITFULL(); RSCALE(t+1); ROT();
.LBB0_1162:
	v_add_f32_e32 v178, v178, v162
	s_add_i32 s60, s50, s44
	v_mfma_f32_32x32x16_bf16 v[50:65], v[142:145], v[170:173], v[50:65]
	v_exp_f32_e32 v82, v82
	v_exp_f32_e32 v83, v83
	ds_read_b64_tr_b16 v[110:111], v174 offset:40960
	ds_read_b64_tr_b16 v[112:113], v174 offset:41472
	v_mfma_f32_32x32x16_bf16 v[34:49], v[142:145], v[114:117], v[34:49]
	v_exp_f32_e32 v84, v84
	v_exp_f32_e32 v85, v85
	ds_read_b64_tr_b16 v[210:211], v174 offset:45056
	ds_read_b64_tr_b16 v[212:213], v174 offset:45568
	v_mfma_f32_32x32x16_bf16 v[50:65], v[138:141], v[118:121], v[50:65]
	v_exp_f32_e32 v86, v86
	v_exp_f32_e32 v87, v87
	ds_read_b64_tr_b16 v[118:119], v174 offset:41984
	ds_read_b64_tr_b16 v[120:121], v174 offset:42496
	v_mfma_f32_32x32x16_bf16 v[34:49], v[138:141], v[122:125], v[34:49]
	v_exp_f32_e32 v88, v88
	v_exp_f32_e32 v89, v89
	ds_read_b64_tr_b16 v[122:123], v174 offset:46080
	ds_read_b64_tr_b16 v[124:125], v174 offset:46592
	s_waitcnt lgkmcnt(14)
	v_mfma_f32_32x32x16_bf16 v[50:65], v[134:137], v[126:129], v[50:65]
	v_exp_f32_e32 v90, v90
	v_exp_f32_e32 v91, v91
	ds_read_b64_tr_b16 v[126:127], v174 offset:43008
	ds_read_b64_tr_b16 v[128:129], v174 offset:43520
	s_waitcnt lgkmcnt(14)
	v_mfma_f32_32x32x16_bf16 v[34:49], v[134:137], v[98:101], v[34:49]
	v_exp_f32_e32 v92, v92
	v_exp_f32_e32 v93, v93
	ds_read_b64_tr_b16 v[98:99], v174 offset:47104
	ds_read_b64_tr_b16 v[100:101], v174 offset:47616
	s_waitcnt lgkmcnt(14)
	v_mfma_f32_32x32x16_bf16 v[50:65], v[130:133], v[102:105], v[50:65]
	v_exp_f32_e32 v94, v94
	v_exp_f32_e32 v95, v95
	ds_read_b64_tr_b16 v[102:103], v174 offset:44032
	ds_read_b64_tr_b16 v[104:105], v174 offset:44544
	s_waitcnt lgkmcnt(14)
	v_mfma_f32_32x32x16_bf16 v[34:49], v[130:133], v[106:109], v[34:49]
	v_exp_f32_e32 v96, v96
	v_exp_f32_e32 v97, v97
	ds_read_b64_tr_b16 v[106:107], v174 offset:48128
	ds_read_b64_tr_b16 v[108:109], v174 offset:48640
	s_add_i32 s12, s47, 0x2000
	s_and_b32 s12, s12, 0x6000
	v_add_u32_e32 v162, s12, v205
	ds_read_b128 v[114:117], v162
	ds_read_b128 v[170:173], v162 offset:512
	ds_read_b128 v[166:169], v162 offset:2048
	ds_read_b128 v[162:165], v162 offset:2560
	s_waitcnt lgkmcnt(14)
	v_mfma_f32_32x32x16_bf16 v[18:33], v[142:145], v[110:113], v[18:33]
	v_exp_f32_e32 v66, v66
	v_exp_f32_e32 v67, v67
	v_mfma_f32_32x32x16_bf16 v[2:17], v[142:145], v[210:213], v[2:17]
	v_exp_f32_e32 v68, v68
	v_exp_f32_e32 v69, v69
	v_mfma_f32_32x32x16_bf16 v[18:33], v[138:141], v[118:121], v[18:33]
	v_exp_f32_e32 v70, v70
	v_exp_f32_e32 v71, v71
	s_waitcnt lgkmcnt(12)
	v_mfma_f32_32x32x16_bf16 v[2:17], v[138:141], v[122:125], v[2:17]
	v_exp_f32_e32 v72, v72
	v_exp_f32_e32 v73, v73
	s_waitcnt lgkmcnt(10)
	v_mfma_f32_32x32x16_bf16 v[18:33], v[134:137], v[126:129], v[18:33]
	v_exp_f32_e32 v74, v74
	v_exp_f32_e32 v75, v75
	s_waitcnt lgkmcnt(8)
	v_mfma_f32_32x32x16_bf16 v[2:17], v[134:137], v[98:101], v[2:17]
	v_exp_f32_e32 v76, v76
	v_exp_f32_e32 v77, v77
	s_waitcnt lgkmcnt(6)
	v_mfma_f32_32x32x16_bf16 v[18:33], v[130:133], v[102:105], v[18:33]
	v_exp_f32_e32 v78, v78
	v_exp_f32_e32 v79, v79
	s_waitcnt lgkmcnt(4)
	v_mfma_f32_32x32x16_bf16 v[2:17], v[130:133], v[106:109], v[2:17]
	v_exp_f32_e32 v80, v80
	v_exp_f32_e32 v81, v81
	s_cmp_eq_u32 s60, -1
	s_cselect_b64 s[12:13], -1, 0
	s_cmp_eq_u32 s59, -1
	s_cselect_b64 s[60:61], -1, 0
	s_waitcnt vmcnt(3) lgkmcnt(0)
	s_barrier
	s_or_b64 s[12:13], s[12:13], s[60:61]
	s_andn2_b64 vcc, exec, s[12:13]
	s_cbranch_vccz .Lrare_1156_3

.Lrare_1156_0:
	ds_read2_b32 v[78:79], v179 offset1:1
	ds_read2_b32 v[80:81], v179 offset0:2 offset1:3
	ds_read2_b32 v[164:165], v179 offset0:8 offset1:9
	ds_read2_b32 v[166:167], v179 offset0:10 offset1:11
	ds_read2_b32 v[168:169], v179 offset0:16 offset1:17
	ds_read2_b32 v[170:171], v179 offset0:18 offset1:19
	ds_read2_b32 v[172:173], v179 offset0:24 offset1:25
	ds_read2_b32 v[180:181], v179 offset0:26 offset1:27
	ds_read2_b32 v[210:211], v179 offset0:32 offset1:33
	ds_read2_b32 v[212:213], v179 offset0:34 offset1:35
	ds_read2_b32 v[214:215], v179 offset0:40 offset1:41
	ds_read2_b32 v[216:217], v179 offset0:42 offset1:43
	s_waitcnt lgkmcnt(11)
	v_pk_add_f32 v[114:115], v[114:115], v[78:79]
	s_waitcnt lgkmcnt(5)
	v_pk_add_f32 v[126:127], v[126:127], v[172:173]
	v_pk_add_f32 v[124:125], v[124:125], v[170:171]
	v_pk_add_f32 v[122:123], v[122:123], v[168:169]
	ds_read2_b32 v[78:79], v179 offset0:48 offset1:49
	ds_read2_b32 v[168:169], v179 offset0:50 offset1:51
	ds_read2_b32 v[170:171], v179 offset0:56 offset1:57
	ds_read2_b32 v[172:173], v179 offset0:58 offset1:59
	s_waitcnt lgkmcnt(8)
	v_pk_add_f32 v[128:129], v[128:129], v[180:181]
	v_pk_add_f32 v[120:121], v[120:121], v[166:167]
	v_pk_add_f32 v[118:119], v[118:119], v[164:165]
	v_pk_add_f32 v[116:117], v[116:117], v[80:81]
	s_waitcnt lgkmcnt(7)
	v_pk_add_f32 v[98:99], v[98:99], v[210:211]
	s_waitcnt lgkmcnt(0)
	v_pk_add_f32 v[112:113], v[112:113], v[172:173]
	v_pk_add_f32 v[110:111], v[110:111], v[170:171]
	v_pk_add_f32 v[108:109], v[108:109], v[168:169]
	v_pk_add_f32 v[106:107], v[106:107], v[78:79]
	v_pk_add_f32 v[104:105], v[104:105], v[216:217]
	v_pk_add_f32 v[102:103], v[102:103], v[214:215]
	v_pk_add_f32 v[100:101], v[100:101], v[212:213]
	s_branch .LBB0_1158
.Lrare_1156_1:
	s_cmp_gt_i32 s44, s55
	s_cselect_b64 vcc, -1, 0
	s_cmp_gt_i32 s44, s48
	s_cselect_b64 s[6:7], -1, 0
	v_cndmask_b32_e64 v74, 0, v203, s[6:7]
	s_cmp_lt_i32 s44, s55
	v_cndmask_b32_e32 v74, v202, v74, vcc
	s_cselect_b64 vcc, -1, 0
	v_cndmask_b32_e32 v75, v0, v202, vcc
	v_sub_f32_e32 v74, v74, v75
	v_exp_f32_e32 v74, v74
	s_nop 0
	v_pk_mul_f32 v[64:65], v[74:75], v[64:65] op_sel_hi:[0,1]
	v_pk_mul_f32 v[62:63], v[74:75], v[62:63] op_sel_hi:[0,1]
	v_pk_mul_f32 v[60:61], v[74:75], v[60:61] op_sel_hi:[0,1]
	v_pk_mul_f32 v[58:59], v[74:75], v[58:59] op_sel_hi:[0,1]
	v_pk_mul_f32 v[56:57], v[74:75], v[56:57] op_sel_hi:[0,1]
	v_pk_mul_f32 v[54:55], v[74:75], v[54:55] op_sel_hi:[0,1]
	v_pk_mul_f32 v[52:53], v[74:75], v[52:53] op_sel_hi:[0,1]
	v_pk_mul_f32 v[50:51], v[74:75], v[50:51] op_sel_hi:[0,1]
	v_pk_mul_f32 v[48:49], v[74:75], v[48:49] op_sel_hi:[0,1]
	v_pk_mul_f32 v[46:47], v[74:75], v[46:47] op_sel_hi:[0,1]
	v_pk_mul_f32 v[44:45], v[74:75], v[44:45] op_sel_hi:[0,1]
	v_pk_mul_f32 v[42:43], v[74:75], v[42:43] op_sel_hi:[0,1]
	v_pk_mul_f32 v[40:41], v[74:75], v[40:41] op_sel_hi:[0,1]
	v_pk_mul_f32 v[38:39], v[74:75], v[38:39] op_sel_hi:[0,1]
	v_pk_mul_f32 v[36:37], v[74:75], v[36:37] op_sel_hi:[0,1]
	v_pk_mul_f32 v[34:35], v[74:75], v[34:35] op_sel_hi:[0,1]
	v_pk_mul_f32 v[32:33], v[74:75], v[32:33] op_sel_hi:[0,1]
	v_pk_mul_f32 v[30:31], v[74:75], v[30:31] op_sel_hi:[0,1]
	v_pk_mul_f32 v[28:29], v[74:75], v[28:29] op_sel_hi:[0,1]
	v_pk_mul_f32 v[26:27], v[74:75], v[26:27] op_sel_hi:[0,1]
	v_pk_mul_f32 v[24:25], v[74:75], v[24:25] op_sel_hi:[0,1]
	v_pk_mul_f32 v[22:23], v[74:75], v[22:23] op_sel_hi:[0,1]
	v_pk_mul_f32 v[20:21], v[74:75], v[20:21] op_sel_hi:[0,1]
	v_pk_mul_f32 v[18:19], v[74:75], v[18:19] op_sel_hi:[0,1]
	v_pk_mul_f32 v[16:17], v[74:75], v[16:17] op_sel_hi:[0,1]
	v_pk_mul_f32 v[14:15], v[74:75], v[14:15] op_sel_hi:[0,1]
	v_pk_mul_f32 v[12:13], v[74:75], v[12:13] op_sel_hi:[0,1]
	v_pk_mul_f32 v[10:11], v[74:75], v[10:11] op_sel_hi:[0,1]
	v_pk_mul_f32 v[8:9], v[74:75], v[8:9] op_sel_hi:[0,1]
	v_pk_mul_f32 v[6:7], v[74:75], v[6:7] op_sel_hi:[0,1]
	v_pk_mul_f32 v[4:5], v[74:75], v[4:5] op_sel_hi:[0,1]
	v_pk_mul_f32 v[2:3], v[74:75], v[2:3] op_sel_hi:[0,1]
	v_mul_f32_e32 v178, v74, v178
	s_branch .LBB0_1160
;   #define RSCALE(t) do{ if(HAS_BIAS&&((t)==tn0||(t)==tn1)){ const float f_=__builtin_amdgcn_exp2f(CREG((t)-1)-CREG(t)); l_reg*=f_; \
;     _Pragma("unroll") for(int d_=0;d_<2*VH;++d_) _Pragma("unroll") for(int r=0;r<16;++r)o[d_][r]*=f_; } }while(0)
;   #define ROT() do{sv_prev=sv_cur;sv_cur=sv_next;sv_next=(sv_next==2*VSL)?0:sv_next+VSL;}while(0)
;   #define WAITFULL() do{ if(VH==1){WAIT_BAR(2);}else{WAIT_BAR(3);} }while(0)
; template<int VH,bool HAS_BIAS,int MODE> __device__ __forceinline__ void attn_unit2(const bf16*Qb,int qp,const bf16*__restrict__ Kb,int kp,const bf16*__restrict__ Vb,int vp,bf16*Ob,int op,int q0,int NT,const float*relb,char*shm,float lam,const float*subg,float gmul){
;     ...
;   for(;t+5<NT;t+=2){
;     STEP(pB0,pB1,pA0,pA1,t,true,true,true);     WAITFULL(); RSCALE(t);   ROT();
;     STEP(pA0,pA1,pB0,pB1,t+1,true,true,true);   WAITFULL(); RSCALE(t+1); ROT();
.Lrare_1156_2:
	ds_read2_b32 v[110:111], v179 offset0:64 offset1:65
	ds_read2_b32 v[112:113], v179 offset0:66 offset1:67
	ds_read2_b32 v[164:165], v179 offset0:72 offset1:73
	ds_read2_b32 v[166:167], v179 offset0:74 offset1:75
	ds_read2_b32 v[168:169], v179 offset0:80 offset1:81
	ds_read2_b32 v[176:177], v179 offset0:82 offset1:83
	ds_read2_b32 v[180:181], v179 offset0:88 offset1:89
	ds_read2_b32 v[210:211], v179 offset0:90 offset1:91
	ds_read2_b32 v[212:213], v179 offset0:96 offset1:97
	ds_read2_b32 v[214:215], v179 offset0:98 offset1:99
	ds_read2_b32 v[216:217], v179 offset0:104 offset1:105
	ds_read2_b32 v[218:219], v179 offset0:106 offset1:107
	s_waitcnt lgkmcnt(11)
	v_pk_add_f32 v[82:83], v[82:83], v[110:111]
	s_waitcnt lgkmcnt(5)
	v_pk_add_f32 v[94:95], v[94:95], v[180:181]
	v_pk_add_f32 v[92:93], v[92:93], v[176:177]
	v_pk_add_f32 v[90:91], v[90:91], v[168:169]
	ds_read2_b32 v[110:111], v179 offset0:112 offset1:113
	ds_read2_b32 v[168:169], v179 offset0:114 offset1:115
	ds_read2_b32 v[176:177], v179 offset0:120 offset1:121
	ds_read2_b32 v[180:181], v179 offset0:122 offset1:123
	s_waitcnt lgkmcnt(8)
	v_pk_add_f32 v[96:97], v[96:97], v[210:211]
	v_pk_add_f32 v[88:89], v[88:89], v[166:167]
	v_pk_add_f32 v[86:87], v[86:87], v[164:165]
	v_pk_add_f32 v[84:85], v[84:85], v[112:113]
	s_waitcnt lgkmcnt(7)
	v_pk_add_f32 v[66:67], v[66:67], v[212:213]
	s_waitcnt lgkmcnt(0)
	v_pk_add_f32 v[80:81], v[80:81], v[180:181]
	v_pk_add_f32 v[78:79], v[78:79], v[176:177]
	v_pk_add_f32 v[76:77], v[76:77], v[168:169]
	v_pk_add_f32 v[74:75], v[74:75], v[110:111]
	v_pk_add_f32 v[72:73], v[72:73], v[218:219]
	v_pk_add_f32 v[70:71], v[70:71], v[216:217]
	v_pk_add_f32 v[68:69], v[68:69], v[214:215]
	s_branch .LBB0_1162
.Lrare_1156_3:
	s_cmp_lt_i32 s44, s55
	s_cselect_b64 vcc, -1, 0
	s_cmp_lt_i32 s79, s55
	v_cndmask_b32_e32 v0, v0, v202, vcc
	v_cndmask_b32_e64 v98, v203, 0, s[6:7]
	s_cselect_b64 vcc, -1, 0
	v_cndmask_b32_e32 v98, v98, v202, vcc
	v_sub_f32_e32 v0, v0, v98
	v_exp_f32_e32 v0, v0
	s_nop 0
	v_pk_mul_f32 v[64:65], v[0:1], v[64:65] op_sel_hi:[0,1]
	v_pk_mul_f32 v[62:63], v[0:1], v[62:63] op_sel_hi:[0,1]
	v_pk_mul_f32 v[60:61], v[0:1], v[60:61] op_sel_hi:[0,1]
	v_pk_mul_f32 v[58:59], v[0:1], v[58:59] op_sel_hi:[0,1]
	v_pk_mul_f32 v[56:57], v[0:1], v[56:57] op_sel_hi:[0,1]
	v_pk_mul_f32 v[54:55], v[0:1], v[54:55] op_sel_hi:[0,1]
	v_pk_mul_f32 v[52:53], v[0:1], v[52:53] op_sel_hi:[0,1]
	v_pk_mul_f32 v[50:51], v[0:1], v[50:51] op_sel_hi:[0,1]
	v_pk_mul_f32 v[48:49], v[0:1], v[48:49] op_sel_hi:[0,1]
	v_pk_mul_f32 v[46:47], v[0:1], v[46:47] op_sel_hi:[0,1]
	v_pk_mul_f32 v[44:45], v[0:1], v[44:45] op_sel_hi:[0,1]
	v_pk_mul_f32 v[42:43], v[0:1], v[42:43] op_sel_hi:[0,1]
	v_pk_mul_f32 v[40:41], v[0:1], v[40:41] op_sel_hi:[0,1]
	v_pk_mul_f32 v[38:39], v[0:1], v[38:39] op_sel_hi:[0,1]
	v_pk_mul_f32 v[36:37], v[0:1], v[36:37] op_sel_hi:[0,1]
	v_pk_mul_f32 v[34:35], v[0:1], v[34:35] op_sel_hi:[0,1]
	v_pk_mul_f32 v[32:33], v[0:1], v[32:33] op_sel_hi:[0,1]
	v_pk_mul_f32 v[30:31], v[0:1], v[30:31] op_sel_hi:[0,1]
	v_pk_mul_f32 v[28:29], v[0:1], v[28:29] op_sel_hi:[0,1]
	v_pk_mul_f32 v[26:27], v[0:1], v[26:27] op_sel_hi:[0,1]
	v_pk_mul_f32 v[24:25], v[0:1], v[24:25] op_sel_hi:[0,1]
	v_pk_mul_f32 v[22:23], v[0:1], v[22:23] op_sel_hi:[0,1]
	v_pk_mul_f32 v[20:21], v[0:1], v[20:21] op_sel_hi:[0,1]
	v_pk_mul_f32 v[18:19], v[0:1], v[18:19] op_sel_hi:[0,1]
	v_pk_mul_f32 v[16:17], v[0:1], v[16:17] op_sel_hi:[0,1]
	v_pk_mul_f32 v[14:15], v[0:1], v[14:15] op_sel_hi:[0,1]
	v_pk_mul_f32 v[12:13], v[0:1], v[12:13] op_sel_hi:[0,1]
	v_pk_mul_f32 v[10:11], v[0:1], v[10:11] op_sel_hi:[0,1]
	v_pk_mul_f32 v[8:9], v[0:1], v[8:9] op_sel_hi:[0,1]
	v_pk_mul_f32 v[6:7], v[0:1], v[6:7] op_sel_hi:[0,1]
	v_pk_mul_f32 v[4:5], v[0:1], v[4:5] op_sel_hi:[0,1]
	v_pk_mul_f32 v[2:3], v[0:1], v[2:3] op_sel_hi:[0,1]
	v_mul_f32_e32 v178, v0, v178
	s_branch .LBB0_1164
